# GEMM1: next tile's 14 prologue LDS-DMA loads issued before the epilogue (reduction words moved to SA(1,1)); prologue waits count the younger epilogue stores
# baseline (speedup 1.0000x reference)
.LBB0_112:
	s_or_b64 exec, exec, s[4:5]
	s_waitcnt lgkmcnt(0)
	s_barrier
	s_load_dword s33, s[0:1], 0xf0
	s_mov_b32 s100, 0
	s_mov_b32 s101, 16
	s_add_u32 s58, s0, 0xa8
	s_addc_u32 s59, s1, 0
	s_add_u32 s4, s0, 0xf0
	s_addc_u32 s5, s1, 0
	s_waitcnt lgkmcnt(0)
	s_abs_i32 s3, s33
	v_cvt_f32_u32_e32 v1, s3
	s_mov_b32 s6, 0
	v_writelane_b32 v255, s4, 0
	v_bfe_u32 v236, v0, 2, 4
	v_rcp_iflag_f32_e32 v1, v1
	v_writelane_b32 v255, s5, 1
	v_writelane_b32 v255, s33, 2
	v_writelane_b32 v255, s6, 3
	v_mul_f32_e32 v1, 0x4f7ffffe, v1
	v_cvt_u32_f32_e32 v1, v1
	s_sub_i32 s6, 0, s3
	s_add_i32 s4, s33, 0x2ff
	s_xor_b32 s5, s4, s33
	v_readfirstlane_b32 s7, v1
	s_mul_i32 s6, s6, s7
	s_mul_hi_u32 s6, s7, s6
	s_abs_i32 s4, s4
	s_add_i32 s7, s7, s6
	s_mul_hi_u32 s6, s4, s7
	s_mul_i32 s7, s6, s3
	s_sub_i32 s4, s4, s7
	s_ashr_i32 s5, s5, 31
	s_add_i32 s7, s6, 1
	s_sub_i32 s8, s4, s3
	s_cmp_ge_u32 s4, s3
	s_cselect_b32 s6, s7, s6
	s_cselect_b32 s4, s8, s4
	s_add_i32 s7, s6, 1
	s_cmp_ge_u32 s4, s3
	s_cselect_b32 s3, s7, s6
	s_xor_b32 s3, s3, s5
	s_sub_i32 s9, s3, s5
	s_cmp_lt_i32 s9, 0
	v_bfe_u32 v239, v0, 2, 2
	v_lshlrev_b32_e32 v238, 4, v0
	v_and_b32_e32 v241, 32, v0
	v_and_b32_e32 v235, 64, v0
	v_lshrrev_b32_e32 v242, 5, v0
	v_lshrrev_b32_e32 v243, 1, v0
	v_lshrrev_b32_e32 v240, 3, v0
	v_and_b32_e32 v197, 15, v0
	v_lshlrev_b32_e32 v237, 6, v0
	v_lshlrev_b32_e32 v199, 11, v236
	s_cbranch_scc1 .LBB0_311
	s_add_u32 s60, s0, 0x78
	s_addc_u32 s61, s1, 0
	s_add_u32 s62, s0, 0x88
	s_addc_u32 s63, s1, 0
	s_add_u32 s64, s0, 0x98
	s_addc_u32 s65, s1, 0
	s_add_u32 s66, s0, 0xa0
	s_addc_u32 s67, s1, 0
	s_add_u32 s68, s0, 0xb0
	s_addc_u32 s69, s1, 0
	s_add_u32 s6, s46, 0x200
	s_addc_u32 s7, s47, 0
	s_add_u32 s74, s46, 0x1000
	s_addc_u32 s75, s47, 0
	s_add_u32 s76, s46, 0x1100
	s_addc_u32 s77, s47, 0
	s_add_u32 s78, s46, 0x1200
	s_addc_u32 s79, s47, 0
	v_writelane_b32 v255, s44, 4
	s_add_u32 s80, s46, 0x1300
	s_addc_u32 s81, s47, 0
	v_writelane_b32 v255, s45, 5
	v_writelane_b32 v255, s6, 6
	s_cmp_eq_u32 s73, 15
	v_bitop3_b32 v5, v238, v241, 48 bitop3:0x6c
	v_writelane_b32 v255, s7, 7
	s_cselect_b64 s[6:7], -1, 0
	v_writelane_b32 v255, s6, 8
	s_cmp_eq_u32 s73, 14
	v_and_or_b32 v7, v242, 4, v239
	v_writelane_b32 v255, s7, 9
	s_cselect_b64 s[6:7], -1, 0
	v_writelane_b32 v255, s6, 10
	s_cmp_eq_u32 s73, 13
	v_and_b32_e32 v1, 24, v243
	v_writelane_b32 v255, s7, 11
	s_cselect_b64 s[6:7], -1, 0
	v_writelane_b32 v255, s6, 12
	s_cmp_eq_u32 s73, 12
	v_or_b32_e32 v6, v5, v235
	v_writelane_b32 v255, s7, 13
	s_cselect_b64 s[6:7], -1, 0
	v_writelane_b32 v255, s6, 14
	s_cmp_eq_u32 s73, 11
	v_or_b32_e32 v2, v7, v1
	v_writelane_b32 v255, s7, 15
	s_cselect_b64 s[6:7], -1, 0
	v_writelane_b32 v255, s6, 16
	s_cmp_eq_u32 s73, 10
	v_and_or_b32 v4, v240, 48, v236
	v_writelane_b32 v255, s7, 17
	s_cselect_b64 s[6:7], -1, 0
	v_writelane_b32 v255, s6, 18
	s_cmp_eq_u32 s73, 9
	v_and_b32_e32 v8, 32, v240
	v_writelane_b32 v255, s7, 19
	s_cselect_b64 s[6:7], -1, 0
	v_writelane_b32 v255, s6, 20
	s_cmp_eq_u32 s73, 8
	v_lshl_or_b32 v138, v4, 11, v6
	v_writelane_b32 v255, s7, 21
	s_cselect_b64 s[6:7], -1, 0
	v_writelane_b32 v255, s6, 22
	s_cmp_eq_u32 s73, 7
	v_or_b32_e32 v4, v2, v8
	v_writelane_b32 v255, s7, 23
	s_cselect_b64 s[6:7], -1, 0
	v_writelane_b32 v255, s6, 24
	s_cmp_eq_u32 s73, 6
	v_or_b32_e32 v9, 0x2000, v238
	v_writelane_b32 v255, s7, 25
	s_cselect_b64 s[6:7], -1, 0
	v_writelane_b32 v255, s6, 26
	s_cmp_eq_u32 s73, 5
	v_lshl_or_b32 v140, v4, 11, v6
	v_writelane_b32 v255, s7, 27
	s_cselect_b64 s[6:7], -1, 0
	v_writelane_b32 v255, s6, 28
	s_cmp_eq_u32 s73, 4
	v_lshrrev_b32_e32 v4, 7, v9
	s_movk_i32 s3, 0x70
	v_writelane_b32 v255, s7, 29
	s_cselect_b64 s[6:7], -1, 0
	s_waitcnt vmcnt(4)
	v_and_or_b32 v10, v4, s3, v236
	v_writelane_b32 v255, s6, 30
	s_cmp_eq_u32 s73, 3
	v_lshl_or_b32 v142, v10, 11, v6
	v_and_b32_e32 v10, 0x60, v4
	v_writelane_b32 v255, s7, 31
	s_cselect_b64 s[6:7], -1, 0
	v_or_b32_e32 v2, v2, v10
	v_writelane_b32 v255, s6, 32
	s_cmp_eq_u32 s73, 2
	v_lshl_or_b32 v144, v2, 11, v6
	v_lshlrev_b32_e32 v209, 1, v1
	v_and_b32_e32 v2, 0x3c0, v237
	v_and_b32_e32 v4, 32, v234
	v_writelane_b32 v255, s7, 33
	s_cselect_b64 s[6:7], -1, 0
	v_bitop3_b32 v210, v209, v4, v2 bitop3:0x36
	v_lshlrev_b32_e32 v2, 4, v16
	v_writelane_b32 v255, s6, 34
	s_cmp_eq_u32 s73, 1
	v_or_b32_e32 v12, 4, v2
	v_or_b32_e32 v14, 8, v2
	v_or_b32_e32 v17, 12, v2
	v_or_b32_e32 v19, 15, v2
	v_writelane_b32 v255, s7, 35
	s_cselect_b64 s[6:7], -1, 0
	v_lshlrev_b32_e32 v11, 10, v16
	v_lshlrev_b32_e32 v13, 6, v12
	v_lshlrev_b32_e32 v15, 6, v14
	v_lshlrev_b32_e32 v18, 6, v17
	v_lshlrev_b32_e32 v20, 6, v19
	v_lshlrev_b32_e32 v2, 5, v16
	v_lshlrev_b32_e32 v16, 8, v16
	s_movk_i32 s3, 0x100
	v_lshlrev_b32_e32 v12, 4, v12
	v_lshlrev_b32_e32 v14, 4, v14
	v_lshlrev_b32_e32 v17, 4, v17
	v_lshlrev_b32_e32 v19, 4, v19
	v_writelane_b32 v255, s6, 36
	s_cmp_eq_u32 s73, 0
	v_bitop3_b32 v16, v16, s3, v197 bitop3:0x36
	v_bitop3_b32 v12, v12, s3, v197 bitop3:0x36
	v_bitop3_b32 v14, v14, s3, v197 bitop3:0x36
	v_bitop3_b32 v17, v17, s3, v197 bitop3:0x36
	v_bitop3_b32 v19, v19, s3, v197 bitop3:0x36
	v_writelane_b32 v255, s7, 37
	s_cselect_b64 s[6:7], -1, 0
	s_lshl_b32 s3, s73, 8
	v_writelane_b32 v255, s6, 38
	s_add_u32 s3, s46, s3
	v_lshrrev_b32_e32 v21, 7, v0
	v_writelane_b32 v255, s7, 39
	s_addc_u32 s6, s47, 0
	s_add_u32 s10, s3, 0x1400
	s_addc_u32 s11, s6, 0
	v_writelane_b32 v255, s10, 40
	v_and_b32_e32 v3, 48, v238
	v_lshl_add_u32 v212, v12, 2, 16
	v_add_u32_e32 v212, 0xc000, v212
	v_writelane_b32 v255, s11, 41
	s_add_u32 s10, s3, 0x2400
	s_addc_u32 s11, s6, 0
	v_writelane_b32 v255, s10, 42
	s_add_u32 s6, s46, 0x3400
	v_lshlrev_b32_e32 v12, 15, v21
	v_writelane_b32 v255, s11, 43
	s_addc_u32 s7, s47, 0
	v_bitop3_b32 v3, v3, v12, v241 bitop3:0xde
	s_load_dwordx2 s[12:13], s[0:1], 0xc8
	s_load_dwordx4 s[48:51], s[0:1], 0x58
	s_load_dwordx4 s[52:55], s[0:1], 0x38
	v_writelane_b32 v255, s6, 44
	v_or3_b32 v148, v3, v199, v235
	v_lshlrev_b32_e32 v3, 4, v9
	s_mov_b32 s3, 0x38000
	v_writelane_b32 v255, s7, 45
	s_add_u32 s6, s46, 0x3500
	v_and_or_b32 v3, v3, s3, v5
	v_bfe_u32 v4, v0, 4, 2
	s_addc_u32 s7, s47, 0
	v_or3_b32 v150, v3, v199, v235
	v_or3_b32 v3, v8, v1, v7
	v_mov_b32_e32 v147, 0
	v_cmp_eq_u32_e64 s[4:5], 0, v4
	v_and_b32_e32 v2, 32, v2
	v_lshlrev_b32_e32 v4, 3, v4
	v_writelane_b32 v255, s6, 46
	v_lshl_add_u32 v22, v197, 2, 16
	v_add_u32_e32 v22, 0xc000, v22
	v_lshl_or_b32 v152, v3, 11, v6
	v_or3_b32 v3, v10, v1, v7
	s_mov_b32 s71, 0
	v_mov_b32_e32 v141, v147
	v_mov_b32_e32 v145, v147
	v_mov_b32_e32 v139, v147
	v_mov_b32_e32 v143, v147
	v_writelane_b32 v255, s7, 47
	v_lshl_add_u32 v211, v16, 2, 16
	v_lshl_add_u32 v213, v14, 2, 16
	v_lshl_add_u32 v214, v17, 2, 16
	v_lshl_add_u32 v215, v19, 2, 16
	v_add_u32_e32 v211, 0xc000, v211
	v_add_u32_e32 v213, 0xc000, v213
	v_add_u32_e32 v214, 0xc000, v214
	v_add_u32_e32 v215, 0xc000, v215
	v_mov_b32_e32 v149, v147
	v_mov_b32_e32 v151, v147
	v_mov_b32_e32 v153, v147
	v_lshl_or_b32 v154, v3, 11, v6
	v_mov_b32_e32 v155, v147
	s_mov_b64 s[90:91], 0x80
	s_mov_b64 s[92:93], 0x40080
	s_mov_b64 s[94:95], 0x100
	s_mov_b64 s[96:97], 0x40100
	s_mov_b64 s[98:99], 0x180
	s_mov_b64 s[6:7], 0x40180
	v_add_u32_e32 v254, v22, v13
	v_add_u32_e32 v208, v22, v15
	v_add_u32_e32 v198, v22, v18
	v_add_u32_e32 v196, v22, v20
	v_lshlrev_b32_e32 v146, 2, v2
	v_lshlrev_b32_e32 v156, 2, v4
	s_mov_b32 s8, 0x3c800000
	s_mov_b32 s11, 0x800000
	v_mbcnt_hi_u32_b32 v220, -1, v176
	v_add_u32_e32 v221, v22, v11
	s_mov_b32 s83, 0
	s_mov_b32 s10, 0x45800000
	s_branch .LBB0_115

.LBB0_197:
	s_load_dwordx2 s[20:21], s[20:21], 0x0
	s_nop 0
	s_load_dwordx2 s[36:37], s[26:27], 0x0
	s_load_dwordx2 vcc, s[24:25], 0x0
	s_lshl_b32 s24, s38, 8
	s_lshl_b32 s26, s88, 8
	v_readfirstlane_b32 s89, v0
	s_lshr_b32 s72, s89, 6
	s_ashr_i32 s25, s24, 31
	s_ashr_i32 s27, s26, 31
	s_lshr_b32 s45, s89, 8
	s_lshl_b32 s82, s72, 10
	s_lshl_b64 s[38:39], s[24:25], 11
	s_lshl_b64 s[86:87], s[26:27], 11
	s_waitcnt lgkmcnt(0)
	s_add_u32 s56, vcc_lo, s86
	s_addc_u32 s57, vcc_hi, s87
	s_add_i32 s27, s82, 16
	s_cmp_eq_u32 s100, 1
	s_cbranch_scc0 .Lg1_nopfpro
	s_mov_b32 s100, 0
	s_add_i32 m0, s27, 0x10000
	v_lshl_add_u64 v[2:3], s[56:57], 0, v[140:141]
	s_add_i32 m0, s27, 0x12000
	s_add_u32 s40, s36, s38
	v_lshl_add_u64 v[4:5], s[56:57], 0, v[144:145]
	s_addc_u32 s41, s37, s39
	s_add_i32 s84, s27, 0x2000
	v_lshl_add_u64 v[8:9], s[40:41], 0, v[138:139]
	s_mov_b32 m0, s27
	s_add_u32 s14, s56, 0x40000
	v_lshl_add_u64 v[6:7], s[40:41], 0, v[142:143]
	s_mov_b32 m0, s84
	s_addc_u32 s15, s57, 0
	s_add_i32 m0, s27, 0x14000
	v_lshl_add_u64 v[10:11], s[14:15], 0, v[140:141]
	s_add_i32 m0, s27, 0x16000
	v_lshl_add_u64 v[10:11], s[14:15], 0, v[144:145]
	s_add_u32 s14, s40, 0x40000
	s_addc_u32 s15, s41, 0
	s_add_i32 s85, s27, 0x4000
	v_lshl_add_u64 v[10:11], s[14:15], 0, v[138:139]
	s_mov_b32 m0, s85
	s_add_i32 s44, s27, 0x6000
	v_lshl_add_u64 v[10:11], s[14:15], 0, v[142:143]
	s_mov_b32 m0, s44
	s_cmp_lg_u32 s45, 1
	s_cbranch_scc1 .Lg1_pf199
	s_barrier
.Lg1_pf199:
	s_lshl_b32 s14, s72, 5
	s_add_i32 m0, s27, 0x18000
	v_lshl_add_u64 v[2:3], v[2:3], 0, s[90:91]
	s_xor_b64 s[28:29], s[28:29], -1
	s_lshl_b32 s19, s45, 6
	v_lshlrev_b32_e32 v11, 2, v197
	s_lshl_b32 s15, s45, 13
	s_and_b32 s25, s14, 0x60
	s_cmp_eq_u32 s101, 16
	s_cbranch_scc1 .Lg1_pfw1
	s_waitcnt vmcnt(18)
	s_branch .Lg1_pfw1j
.Lg1_pfw1:
	s_waitcnt vmcnt(26)
.Lg1_pfw1j:
	s_barrier
	v_lshl_add_u64 v[2:3], v[4:5], 0, s[90:91]
	s_add_i32 m0, s27, 0x1a000
	s_add_i32 s45, s27, 0x8000
	s_add_i32 s72, s27, 0xa000
	v_lshl_or_b32 v10, v197, 6, v209
	v_and_b32_e32 v11, 32, v11
	v_lshl_add_u64 v[2:3], v[8:9], 0, s[90:91]
	s_mov_b32 m0, s45
	s_add_u32 s14, s56, 0x40080
	v_bitop3_b32 v10, v10, s15, v11 bitop3:0xde
	v_lshl_add_u64 v[2:3], v[6:7], 0, s[90:91]
	s_mov_b32 m0, s72
	s_addc_u32 s15, s57, 0
	s_add_i32 m0, s27, 0x1c000
	v_lshl_add_u64 v[2:3], s[14:15], 0, v[140:141]
	v_lshl_add_u64 v[2:3], s[14:15], 0, v[144:145]
	s_add_i32 m0, s27, 0x1e000
	v_add_u32_e32 v157, 16, v10
	v_lshl_add_u64 v[2:3], s[36:37], 0, v[148:149]
	v_lshl_add_u64 v[130:131], v[2:3], 0, s[38:39]
	v_lshl_add_u64 v[2:3], s[36:37], 0, v[150:151]
	v_lshl_add_u64 v[132:133], v[2:3], 0, s[38:39]
	v_lshl_add_u64 v[2:3], vcc, 0, v[152:153]
	s_cmp_eq_u32 s101, 16
	s_cbranch_scc1 .Lg1_pfw2
	s_waitcnt vmcnt(14)
	s_branch .Lg1_pfw2j
.Lg1_pfw2:
	s_waitcnt vmcnt(22)
.Lg1_pfw2j:
	s_mov_b32 s101, 16
	s_branch .Lg1_join2
.Lg1_nopfpro:
	s_add_i32 m0, s27, 0x10000
	v_lshl_add_u64 v[2:3], s[56:57], 0, v[140:141]
	global_load_lds_dwordx4 v[2:3], off
	s_add_i32 m0, s27, 0x12000
	s_add_u32 s40, s36, s38
	v_lshl_add_u64 v[4:5], s[56:57], 0, v[144:145]
	s_addc_u32 s41, s37, s39
	s_add_i32 s84, s27, 0x2000
	global_load_lds_dwordx4 v[4:5], off
	v_lshl_add_u64 v[8:9], s[40:41], 0, v[138:139]
	s_mov_b32 m0, s27
	s_add_u32 s14, s56, 0x40000
	global_load_lds_dwordx4 v[8:9], off
	v_lshl_add_u64 v[6:7], s[40:41], 0, v[142:143]
	s_mov_b32 m0, s84
	s_addc_u32 s15, s57, 0
	global_load_lds_dwordx4 v[6:7], off
	s_add_i32 m0, s27, 0x14000
	v_lshl_add_u64 v[10:11], s[14:15], 0, v[140:141]
	global_load_lds_dwordx4 v[10:11], off
	s_add_i32 m0, s27, 0x16000
	v_lshl_add_u64 v[10:11], s[14:15], 0, v[144:145]
	s_add_u32 s14, s40, 0x40000
	s_addc_u32 s15, s41, 0
	s_add_i32 s85, s27, 0x4000
	global_load_lds_dwordx4 v[10:11], off
	v_lshl_add_u64 v[10:11], s[14:15], 0, v[138:139]
	s_mov_b32 m0, s85
	s_add_i32 s44, s27, 0x6000
	global_load_lds_dwordx4 v[10:11], off
	v_lshl_add_u64 v[10:11], s[14:15], 0, v[142:143]
	s_mov_b32 m0, s44
	s_cmp_lg_u32 s45, 1
	global_load_lds_dwordx4 v[10:11], off
	s_cbranch_scc1 .LBB0_199
	s_barrier

.Lg1_join2:
	v_lshl_add_u64 v[134:135], v[2:3], 0, s[86:87]
	v_lshl_add_u64 v[2:3], vcc, 0, v[154:155]
	v_lshl_add_u64 v[136:137], v[2:3], 0, s[86:87]
	v_mov_b32_e32 v2, 0
	s_mov_b32 s36, -2
	s_mov_b64 vcc, 0
	v_mov_b32_e32 v3, v2
	v_mov_b32_e32 v4, v2
	v_mov_b32_e32 v5, v2
	v_mov_b32_e32 v6, v2
	v_mov_b32_e32 v7, v2
	v_mov_b32_e32 v8, v2
	v_mov_b32_e32 v9, v2
	v_mov_b32_e32 v10, v2
	v_mov_b32_e32 v11, v2
	v_mov_b32_e32 v12, v2
	v_mov_b32_e32 v13, v2
	v_mov_b32_e32 v14, v2
	v_mov_b32_e32 v15, v2
	v_mov_b32_e32 v16, v2
	v_mov_b32_e32 v17, v2
	v_mov_b32_e32 v18, v2
	v_mov_b32_e32 v19, v2
	v_mov_b32_e32 v20, v2
	v_mov_b32_e32 v21, v2
	v_mov_b32_e32 v22, v2
	v_mov_b32_e32 v23, v2
	v_mov_b32_e32 v24, v2
	v_mov_b32_e32 v25, v2
	v_mov_b32_e32 v26, v2
	v_mov_b32_e32 v27, v2
	v_mov_b32_e32 v28, v2
	v_mov_b32_e32 v29, v2
	v_mov_b32_e32 v30, v2
	v_mov_b32_e32 v31, v2
	v_mov_b32_e32 v32, v2
	v_mov_b32_e32 v33, v2
	v_mov_b32_e32 v34, v2
	v_mov_b32_e32 v35, v2
	v_mov_b32_e32 v36, v2
	v_mov_b32_e32 v37, v2
	v_mov_b32_e32 v38, v2
	v_mov_b32_e32 v39, v2
	v_mov_b32_e32 v40, v2
	v_mov_b32_e32 v41, v2
	v_mov_b32_e32 v42, v2
	v_mov_b32_e32 v43, v2
	v_mov_b32_e32 v44, v2
	v_mov_b32_e32 v45, v2
	v_mov_b32_e32 v46, v2
	v_mov_b32_e32 v47, v2
	v_mov_b32_e32 v48, v2
	v_mov_b32_e32 v49, v2
	v_mov_b32_e32 v50, v2
	v_mov_b32_e32 v51, v2
	v_mov_b32_e32 v52, v2
	v_mov_b32_e32 v53, v2
	v_mov_b32_e32 v54, v2
	v_mov_b32_e32 v55, v2
	v_mov_b32_e32 v56, v2
	v_mov_b32_e32 v57, v2
	v_mov_b32_e32 v58, v2
	v_mov_b32_e32 v59, v2
	v_mov_b32_e32 v60, v2
	v_mov_b32_e32 v61, v2
	v_mov_b32_e32 v62, v2
	v_mov_b32_e32 v63, v2
	v_mov_b32_e32 v64, v2
	v_mov_b32_e32 v65, v2
	v_mov_b32_e32 v66, v2
	v_mov_b32_e32 v67, v2
	v_mov_b32_e32 v68, v2
	v_mov_b32_e32 v69, v2
	v_mov_b32_e32 v70, v2
	v_mov_b32_e32 v71, v2
	v_mov_b32_e32 v72, v2
	v_mov_b32_e32 v73, v2
	v_mov_b32_e32 v74, v2
	v_mov_b32_e32 v75, v2
	v_mov_b32_e32 v76, v2
	v_mov_b32_e32 v77, v2
	v_mov_b32_e32 v78, v2
	v_mov_b32_e32 v79, v2
	v_mov_b32_e32 v80, v2
	v_mov_b32_e32 v81, v2
	v_mov_b32_e32 v82, v2
	v_mov_b32_e32 v83, v2
	v_mov_b32_e32 v84, v2
	v_mov_b32_e32 v85, v2
	v_mov_b32_e32 v86, v2
	v_mov_b32_e32 v87, v2
	v_mov_b32_e32 v88, v2
	v_mov_b32_e32 v89, v2
	v_mov_b32_e32 v90, v2
	v_mov_b32_e32 v91, v2
	v_mov_b32_e32 v92, v2
	v_mov_b32_e32 v93, v2
	v_mov_b32_e32 v94, v2
	v_mov_b32_e32 v95, v2
	v_mov_b32_e32 v96, v2
	v_mov_b32_e32 v97, v2
	v_mov_b32_e32 v98, v2
	v_mov_b32_e32 v99, v2
	v_mov_b32_e32 v100, v2
	v_mov_b32_e32 v101, v2
	v_mov_b32_e32 v102, v2
	v_mov_b32_e32 v103, v2
	v_mov_b32_e32 v104, v2
	v_mov_b32_e32 v105, v2
	v_mov_b32_e32 v106, v2
	v_mov_b32_e32 v107, v2
	v_mov_b32_e32 v108, v2
	v_mov_b32_e32 v109, v2
	v_mov_b32_e32 v110, v2
	v_mov_b32_e32 v111, v2
	v_mov_b32_e32 v112, v2
	v_mov_b32_e32 v113, v2
	v_mov_b32_e32 v114, v2
	v_mov_b32_e32 v115, v2
	v_mov_b32_e32 v116, v2
	v_mov_b32_e32 v117, v2
	v_mov_b32_e32 v118, v2
	v_mov_b32_e32 v119, v2
	v_mov_b32_e32 v120, v2
	v_mov_b32_e32 v121, v2
	v_mov_b32_e32 v122, v2
	v_mov_b32_e32 v123, v2
	v_mov_b32_e32 v124, v2
	v_mov_b32_e32 v125, v2
	v_mov_b32_e32 v126, v2
	v_mov_b32_e32 v127, v2
	v_mov_b32_e32 v128, v2
	v_mov_b32_e32 v129, v2
	v_lshl_or_b32 v158, s25, 7, v210
	s_barrier

.LBB0_203:
	s_cmpk_lg_u32 s33, 0x100
	s_cbranch_scc1 .Lg1_nopf
	s_add_i32 s14, s83, 1
	s_cmp_lt_i32 s14, s9
	s_cbranch_scc0 .Lg1_nopf
	s_add_u32 vcc_lo, s56, 0x200000
	s_addc_u32 vcc_hi, s57, 0
	s_add_i32 m0, s27, 0x10000
	v_lshl_add_u64 v[160:161], vcc, 0, v[140:141]
	global_load_lds_dwordx4 v[160:161], off
	s_add_i32 m0, s27, 0x12000
	v_lshl_add_u64 v[162:163], vcc, 0, v[144:145]
	global_load_lds_dwordx4 v[162:163], off
	s_mov_b32 m0, s27
	v_lshl_add_u64 v[164:165], s[40:41], 0, v[138:139]
	global_load_lds_dwordx4 v[164:165], off
	s_add_i32 m0, s27, 0x2000
	v_lshl_add_u64 v[166:167], s[40:41], 0, v[142:143]
	global_load_lds_dwordx4 v[166:167], off
	s_add_u32 s14, vcc_lo, 0x40000
	s_addc_u32 s15, vcc_hi, 0
	s_add_i32 m0, s27, 0x14000
	v_lshl_add_u64 v[160:161], s[14:15], 0, v[140:141]
	global_load_lds_dwordx4 v[160:161], off
	s_add_i32 m0, s27, 0x16000
	v_lshl_add_u64 v[162:163], s[14:15], 0, v[144:145]
	global_load_lds_dwordx4 v[162:163], off
	s_add_u32 s14, s40, 0x40000
	s_addc_u32 s15, s41, 0
	s_add_i32 m0, s27, 0x4000
	v_lshl_add_u64 v[164:165], s[14:15], 0, v[138:139]
	global_load_lds_dwordx4 v[164:165], off
	s_add_i32 m0, s27, 0x6000
	v_lshl_add_u64 v[166:167], s[14:15], 0, v[142:143]
	global_load_lds_dwordx4 v[166:167], off
	s_add_u32 s14, vcc_lo, 0x80
	s_addc_u32 s15, vcc_hi, 0
	s_add_i32 m0, s27, 0x18000
	v_lshl_add_u64 v[160:161], s[14:15], 0, v[140:141]
	global_load_lds_dwordx4 v[160:161], off
	s_add_i32 m0, s27, 0x1a000
	v_lshl_add_u64 v[162:163], s[14:15], 0, v[144:145]
	global_load_lds_dwordx4 v[162:163], off
	s_add_u32 s14, s40, 0x80
	s_addc_u32 s15, s41, 0
	s_add_i32 m0, s27, 0x8000
	v_lshl_add_u64 v[164:165], s[14:15], 0, v[138:139]
	global_load_lds_dwordx4 v[164:165], off
	s_add_i32 m0, s27, 0xa000
	v_lshl_add_u64 v[166:167], s[14:15], 0, v[142:143]
	global_load_lds_dwordx4 v[166:167], off
	s_add_u32 s14, vcc_lo, 0x40080
	s_addc_u32 s15, vcc_hi, 0
	s_add_i32 m0, s27, 0x1c000
	v_lshl_add_u64 v[160:161], s[14:15], 0, v[140:141]
	global_load_lds_dwordx4 v[160:161], off
	s_add_i32 m0, s27, 0x1e000
	v_lshl_add_u64 v[162:163], s[14:15], 0, v[144:145]
	global_load_lds_dwordx4 v[162:163], off
	s_mov_b32 s100, 1
	s_mov_b32 s101, 16

.LBB0_305:
	s_and_b64 vcc, exec, s[24:25]
	s_cbranch_vccz .LBB0_170
	s_mov_b32 s101, 8
	v_mul_f32_e32 v130, 0xbfb8aa3b, v126
	v_mul_f32_e32 v131, 0xbfb8aa3b, v127
	v_exp_f32_e32 v130, v130
	v_exp_f32_e32 v131, v131
	s_cmp_eq_u32 s88, 2
	s_cselect_b32 s70, 0x100, 0
	v_add_f32_e32 v130, 1.0, v130
	v_add_f32_e32 v131, 1.0, v131
	v_rcp_f32_e32 v130, v130
	v_rcp_f32_e32 v131, v131
	v_and_b32_e32 v132, 0x78, v178
	v_ashrrev_i32_e32 v159, 31, v158
	s_mov_b32 s14, 0x10000
	v_pk_mul_f32 v[126:127], v[126:127], v[130:131]
	s_nop 0
	v_pk_mul_f32 v[122:123], v[122:123], v[126:127]
	s_nop 0
	v_cvt_pk_bf16_f32 v122, v122, v123
	v_mul_f32_e32 v123, 0xbfb8aa3b, v128
	v_exp_f32_e32 v123, v123
	s_nop 0
	v_add_f32_e32 v123, 1.0, v123
	v_rcp_f32_e32 v126, v123
	v_mul_f32_e32 v123, 0xbfb8aa3b, v129
	v_exp_f32_e32 v123, v123
	s_nop 0
	v_add_f32_e32 v123, 1.0, v123
	v_rcp_f32_e32 v127, v123
	s_nop 0
	v_pk_mul_f32 v[126:127], v[128:129], v[126:127]
	s_nop 0
	v_pk_mul_f32 v[124:125], v[124:125], v[126:127]
	s_nop 0
	v_cvt_pk_bf16_f32 v123, v124, v125
	v_mul_f32_e32 v124, 0xbfb8aa3b, v118
	v_mul_f32_e32 v125, 0xbfb8aa3b, v119
	v_exp_f32_e32 v124, v124
	v_exp_f32_e32 v125, v125
	v_add_f32_e32 v124, 1.0, v124
	v_add_f32_e32 v125, 1.0, v125
	v_rcp_f32_e32 v124, v124
	v_rcp_f32_e32 v125, v125
	s_nop 0
	v_pk_mul_f32 v[118:119], v[118:119], v[124:125]
	s_nop 0
	v_pk_mul_f32 v[114:115], v[114:115], v[118:119]
	v_mul_f32_e32 v118, 0xbfb8aa3b, v110
	v_mul_f32_e32 v119, 0xbfb8aa3b, v111
	v_exp_f32_e32 v118, v118
	v_exp_f32_e32 v119, v119
	v_cvt_pk_bf16_f32 v124, v114, v115
	v_mul_f32_e32 v114, 0xbfb8aa3b, v120
	v_add_f32_e32 v118, 1.0, v118
	v_add_f32_e32 v119, 1.0, v119
	v_rcp_f32_e32 v118, v118
	v_rcp_f32_e32 v119, v119
	v_mul_f32_e32 v115, 0xbfb8aa3b, v121
	v_exp_f32_e32 v114, v114
	v_exp_f32_e32 v115, v115
	v_pk_mul_f32 v[110:111], v[110:111], v[118:119]
	v_add_f32_e32 v114, 1.0, v114
	v_pk_mul_f32 v[106:107], v[106:107], v[110:111]
	v_add_f32_e32 v115, 1.0, v115
	v_cvt_pk_bf16_f32 v106, v106, v107
	v_mul_f32_e32 v107, 0xbfb8aa3b, v112
	v_exp_f32_e32 v107, v107
	v_rcp_f32_e32 v114, v114
	v_rcp_f32_e32 v115, v115
	v_add_f32_e32 v107, 1.0, v107
	v_rcp_f32_e32 v110, v107
	v_mul_f32_e32 v107, 0xbfb8aa3b, v113
	v_exp_f32_e32 v107, v107
	v_pk_mul_f32 v[114:115], v[120:121], v[114:115]
	v_add_f32_e32 v107, 1.0, v107
	v_rcp_f32_e32 v111, v107
	v_pk_mul_f32 v[114:115], v[116:117], v[114:115]
	v_lshlrev_b32_e32 v116, 1, v132
	v_mov_b32_e32 v117, v147
	v_pk_mul_f32 v[110:111], v[112:113], v[110:111]
	v_cvt_pk_bf16_f32 v125, v114, v115
	v_pk_mul_f32 v[108:109], v[108:109], v[110:111]
	v_lshlrev_b64 v[114:115], 9, v[158:159]
	v_cvt_pk_bf16_f32 v107, v108, v109
	v_mul_f32_e32 v108, 0xbfb8aa3b, v102
	v_mul_f32_e32 v109, 0xbfb8aa3b, v103
	v_exp_f32_e32 v108, v108
	v_exp_f32_e32 v109, v109
	v_lshl_add_u64 v[114:115], s[12:13], 0, v[114:115]
	v_lshl_add_u64 v[114:115], v[114:115], 0, s[70:71]
	v_add_f32_e32 v108, 1.0, v108
	v_add_f32_e32 v109, 1.0, v109
	v_rcp_f32_e32 v108, v108
	v_rcp_f32_e32 v109, v109
	v_lshl_add_u64 v[114:115], v[114:115], 0, v[116:117]
	global_store_dwordx4 v[114:115], v[122:125], off
	v_pk_mul_f32 v[102:103], v[102:103], v[108:109]
	s_nop 0
	v_pk_mul_f32 v[98:99], v[98:99], v[102:103]
	s_nop 0
	v_cvt_pk_bf16_f32 v108, v98, v99
	v_mul_f32_e32 v98, 0xbfb8aa3b, v104
	v_mul_f32_e32 v99, 0xbfb8aa3b, v105
	v_exp_f32_e32 v98, v98
	v_exp_f32_e32 v99, v99
	v_add_f32_e32 v98, 1.0, v98
	v_add_f32_e32 v99, 1.0, v99
	v_rcp_f32_e32 v98, v98
	v_rcp_f32_e32 v99, v99
	s_nop 0
	v_pk_mul_f32 v[98:99], v[104:105], v[98:99]
	s_nop 0
	v_pk_mul_f32 v[98:99], v[100:101], v[98:99]
	s_nop 0
	v_cvt_pk_bf16_f32 v109, v98, v99
	v_or_b32_e32 v98, 16, v158
	v_ashrrev_i32_e32 v99, 31, v98
	v_lshlrev_b64 v[98:99], 9, v[98:99]
	v_lshl_add_u64 v[98:99], s[12:13], 0, v[98:99]
	v_lshl_add_u64 v[98:99], v[98:99], 0, s[70:71]
	v_lshl_add_u64 v[98:99], v[98:99], 0, v[116:117]
	global_store_dwordx4 v[98:99], v[106:109], off
	v_mul_f32_e32 v98, 0xbfb8aa3b, v94
	v_mul_f32_e32 v99, 0xbfb8aa3b, v95
	v_exp_f32_e32 v98, v98
	v_exp_f32_e32 v99, v99
	v_add_f32_e32 v98, 1.0, v98
	v_add_f32_e32 v99, 1.0, v99
	v_rcp_f32_e32 v98, v98
	v_rcp_f32_e32 v99, v99
	s_nop 0
	v_pk_mul_f32 v[94:95], v[94:95], v[98:99]
	s_nop 0
	v_pk_mul_f32 v[90:91], v[90:91], v[94:95]
	s_nop 0
	v_cvt_pk_bf16_f32 v90, v90, v91
	v_mul_f32_e32 v91, 0xbfb8aa3b, v96
	v_exp_f32_e32 v91, v91
	s_nop 0
	v_add_f32_e32 v91, 1.0, v91
	v_rcp_f32_e32 v94, v91
	v_mul_f32_e32 v91, 0xbfb8aa3b, v97
	v_exp_f32_e32 v91, v91
	s_nop 0
	v_add_f32_e32 v91, 1.0, v91
	v_rcp_f32_e32 v95, v91
	s_nop 0
	v_pk_mul_f32 v[94:95], v[96:97], v[94:95]
	s_nop 0
	v_pk_mul_f32 v[92:93], v[92:93], v[94:95]
	s_nop 0
	v_cvt_pk_bf16_f32 v91, v92, v93
	v_mul_f32_e32 v92, 0xbfb8aa3b, v86
	v_mul_f32_e32 v93, 0xbfb8aa3b, v87
	v_exp_f32_e32 v92, v92
	v_exp_f32_e32 v93, v93
	v_add_f32_e32 v92, 1.0, v92
	v_add_f32_e32 v93, 1.0, v93
	v_rcp_f32_e32 v92, v92
	v_rcp_f32_e32 v93, v93
	s_nop 0
	v_pk_mul_f32 v[86:87], v[86:87], v[92:93]
	s_nop 0
	v_pk_mul_f32 v[82:83], v[82:83], v[86:87]
	s_nop 0
	v_cvt_pk_bf16_f32 v92, v82, v83
	v_mul_f32_e32 v82, 0xbfb8aa3b, v88
	v_mul_f32_e32 v83, 0xbfb8aa3b, v89
	v_exp_f32_e32 v82, v82
	v_exp_f32_e32 v83, v83
	v_add_f32_e32 v82, 1.0, v82
	v_add_f32_e32 v83, 1.0, v83
	v_rcp_f32_e32 v82, v82
	v_rcp_f32_e32 v83, v83
	s_nop 0
	v_pk_mul_f32 v[82:83], v[88:89], v[82:83]
	s_nop 0
	v_pk_mul_f32 v[82:83], v[84:85], v[82:83]
	s_nop 0
	v_cvt_pk_bf16_f32 v93, v82, v83
	v_or_b32_e32 v82, 32, v158
	v_ashrrev_i32_e32 v83, 31, v82
	v_lshlrev_b64 v[82:83], 9, v[82:83]
	v_lshl_add_u64 v[82:83], s[12:13], 0, v[82:83]
	v_lshl_add_u64 v[82:83], v[82:83], 0, s[70:71]
	v_lshl_add_u64 v[82:83], v[82:83], 0, v[116:117]
	global_store_dwordx4 v[82:83], v[90:93], off
	v_mul_f32_e32 v82, 0xbfb8aa3b, v78
	v_mul_f32_e32 v83, 0xbfb8aa3b, v79
	v_exp_f32_e32 v82, v82
	v_exp_f32_e32 v83, v83
	v_add_f32_e32 v82, 1.0, v82
	v_add_f32_e32 v83, 1.0, v83
	v_rcp_f32_e32 v82, v82
	v_rcp_f32_e32 v83, v83
	s_nop 0
	v_pk_mul_f32 v[78:79], v[78:79], v[82:83]
	s_nop 0
	v_pk_mul_f32 v[74:75], v[74:75], v[78:79]
	s_nop 0
	v_cvt_pk_bf16_f32 v74, v74, v75
	v_mul_f32_e32 v75, 0xbfb8aa3b, v80
	v_exp_f32_e32 v75, v75
	s_nop 0
	v_add_f32_e32 v75, 1.0, v75
	v_rcp_f32_e32 v78, v75
	v_mul_f32_e32 v75, 0xbfb8aa3b, v81
	v_exp_f32_e32 v75, v75
	s_nop 0
	v_add_f32_e32 v75, 1.0, v75
	v_rcp_f32_e32 v79, v75
	s_nop 0
	v_pk_mul_f32 v[78:79], v[80:81], v[78:79]
	s_nop 0
	v_pk_mul_f32 v[76:77], v[76:77], v[78:79]
	s_nop 0
	v_cvt_pk_bf16_f32 v75, v76, v77
	v_mul_f32_e32 v76, 0xbfb8aa3b, v70
	v_mul_f32_e32 v77, 0xbfb8aa3b, v71
	v_exp_f32_e32 v76, v76
	v_exp_f32_e32 v77, v77
	v_add_f32_e32 v76, 1.0, v76
	v_add_f32_e32 v77, 1.0, v77
	v_rcp_f32_e32 v76, v76
	v_rcp_f32_e32 v77, v77
	s_nop 0
	v_pk_mul_f32 v[70:71], v[70:71], v[76:77]
	s_nop 0
	v_pk_mul_f32 v[66:67], v[66:67], v[70:71]
	s_nop 0
	v_cvt_pk_bf16_f32 v76, v66, v67
	v_mul_f32_e32 v66, 0xbfb8aa3b, v72
	v_mul_f32_e32 v67, 0xbfb8aa3b, v73
	v_exp_f32_e32 v66, v66
	v_exp_f32_e32 v67, v67
	v_add_f32_e32 v66, 1.0, v66
	v_add_f32_e32 v67, 1.0, v67
	v_rcp_f32_e32 v66, v66
	v_rcp_f32_e32 v67, v67
	s_nop 0
	v_pk_mul_f32 v[66:67], v[72:73], v[66:67]
	s_nop 0
	v_pk_mul_f32 v[66:67], v[68:69], v[66:67]
	s_nop 0
	v_cvt_pk_bf16_f32 v77, v66, v67
	v_or_b32_e32 v66, 48, v158
	v_ashrrev_i32_e32 v67, 31, v66
	v_lshlrev_b64 v[66:67], 9, v[66:67]
	v_lshl_add_u64 v[66:67], s[12:13], 0, v[66:67]
	v_lshl_add_u64 v[66:67], v[66:67], 0, s[70:71]
	v_lshl_add_u64 v[66:67], v[66:67], 0, v[116:117]
	global_store_dwordx4 v[66:67], v[74:77], off
	v_mul_f32_e32 v66, 0xbfb8aa3b, v62
	v_mul_f32_e32 v67, 0xbfb8aa3b, v63
	v_exp_f32_e32 v66, v66
	v_exp_f32_e32 v67, v67
	v_add_f32_e32 v66, 1.0, v66
	v_add_f32_e32 v67, 1.0, v67
	v_rcp_f32_e32 v66, v66
	v_rcp_f32_e32 v67, v67
	s_nop 0
	v_pk_mul_f32 v[62:63], v[62:63], v[66:67]
	s_nop 0
	v_pk_mul_f32 v[58:59], v[58:59], v[62:63]
	s_nop 0
	v_cvt_pk_bf16_f32 v58, v58, v59
	v_mul_f32_e32 v59, 0xbfb8aa3b, v64
	v_exp_f32_e32 v59, v59
	s_nop 0
	v_add_f32_e32 v59, 1.0, v59
	v_rcp_f32_e32 v62, v59
	v_mul_f32_e32 v59, 0xbfb8aa3b, v65
	v_exp_f32_e32 v59, v59
	s_nop 0
	v_add_f32_e32 v59, 1.0, v59
	v_rcp_f32_e32 v63, v59
	s_nop 0
	v_pk_mul_f32 v[62:63], v[64:65], v[62:63]
	s_nop 0
	v_pk_mul_f32 v[60:61], v[60:61], v[62:63]
	s_nop 0
	v_cvt_pk_bf16_f32 v59, v60, v61
	v_mul_f32_e32 v60, 0xbfb8aa3b, v54
	v_mul_f32_e32 v61, 0xbfb8aa3b, v55
	v_exp_f32_e32 v60, v60
	v_exp_f32_e32 v61, v61
	v_add_f32_e32 v60, 1.0, v60
	v_add_f32_e32 v61, 1.0, v61
	v_rcp_f32_e32 v60, v60
	v_rcp_f32_e32 v61, v61
	s_nop 0
	v_pk_mul_f32 v[54:55], v[54:55], v[60:61]
	s_nop 0
	v_pk_mul_f32 v[50:51], v[50:51], v[54:55]
	s_nop 0
	v_cvt_pk_bf16_f32 v60, v50, v51
	v_mul_f32_e32 v50, 0xbfb8aa3b, v56
	v_mul_f32_e32 v51, 0xbfb8aa3b, v57
	v_exp_f32_e32 v50, v50
	v_exp_f32_e32 v51, v51
	v_add_f32_e32 v50, 1.0, v50
	v_add_f32_e32 v51, 1.0, v51
	v_rcp_f32_e32 v50, v50
	v_rcp_f32_e32 v51, v51
	s_nop 0
	v_pk_mul_f32 v[50:51], v[56:57], v[50:51]
	s_nop 0
	v_pk_mul_f32 v[50:51], v[52:53], v[50:51]
	s_nop 0
	v_cvt_pk_bf16_f32 v61, v50, v51
	v_add_co_u32_e32 v50, vcc, s14, v114
	s_mov_b32 s14, 0x12000
	s_nop 0
	v_addc_co_u32_e32 v51, vcc, 0, v115, vcc
	global_store_dwordx4 v[50:51], v[58:61], off
	v_mul_f32_e32 v50, 0xbfb8aa3b, v46
	v_mul_f32_e32 v51, 0xbfb8aa3b, v47
	v_exp_f32_e32 v50, v50
	v_exp_f32_e32 v51, v51
	v_add_f32_e32 v50, 1.0, v50
	v_add_f32_e32 v51, 1.0, v51
	v_rcp_f32_e32 v50, v50
	v_rcp_f32_e32 v51, v51
	s_nop 0
	v_pk_mul_f32 v[46:47], v[46:47], v[50:51]
	s_nop 0
	v_pk_mul_f32 v[42:43], v[42:43], v[46:47]
	s_nop 0
	v_cvt_pk_bf16_f32 v42, v42, v43
	v_mul_f32_e32 v43, 0xbfb8aa3b, v48
	v_exp_f32_e32 v43, v43
	s_nop 0
	v_add_f32_e32 v43, 1.0, v43
	v_rcp_f32_e32 v46, v43
	v_mul_f32_e32 v43, 0xbfb8aa3b, v49
	v_exp_f32_e32 v43, v43
	s_nop 0
	v_add_f32_e32 v43, 1.0, v43
	v_rcp_f32_e32 v47, v43
	s_nop 0
	v_pk_mul_f32 v[46:47], v[48:49], v[46:47]
	s_nop 0
	v_pk_mul_f32 v[44:45], v[44:45], v[46:47]
	s_nop 0
	v_cvt_pk_bf16_f32 v43, v44, v45
	v_mul_f32_e32 v44, 0xbfb8aa3b, v38
	v_mul_f32_e32 v45, 0xbfb8aa3b, v39
	v_exp_f32_e32 v44, v44
	v_exp_f32_e32 v45, v45
	v_add_f32_e32 v44, 1.0, v44
	v_add_f32_e32 v45, 1.0, v45
	v_rcp_f32_e32 v44, v44
	v_rcp_f32_e32 v45, v45
	s_nop 0
	v_pk_mul_f32 v[38:39], v[38:39], v[44:45]
	s_nop 0
	v_pk_mul_f32 v[34:35], v[34:35], v[38:39]
	s_nop 0
	v_cvt_pk_bf16_f32 v44, v34, v35
	v_mul_f32_e32 v34, 0xbfb8aa3b, v40
	v_mul_f32_e32 v35, 0xbfb8aa3b, v41
	v_exp_f32_e32 v34, v34
	v_exp_f32_e32 v35, v35
	v_add_f32_e32 v34, 1.0, v34
	v_add_f32_e32 v35, 1.0, v35
	v_rcp_f32_e32 v34, v34
	v_rcp_f32_e32 v35, v35
	s_nop 0
	v_pk_mul_f32 v[34:35], v[40:41], v[34:35]
	s_nop 0
	v_pk_mul_f32 v[34:35], v[36:37], v[34:35]
	s_nop 0
	v_cvt_pk_bf16_f32 v45, v34, v35
	v_add_co_u32_e32 v34, vcc, s14, v114
	s_mov_b32 s14, 0x14000
	s_nop 0
	v_addc_co_u32_e32 v35, vcc, 0, v115, vcc
	global_store_dwordx4 v[34:35], v[42:45], off
	v_mul_f32_e32 v34, 0xbfb8aa3b, v30
	v_mul_f32_e32 v35, 0xbfb8aa3b, v31
	v_exp_f32_e32 v34, v34
	v_exp_f32_e32 v35, v35
	v_add_f32_e32 v34, 1.0, v34
	v_add_f32_e32 v35, 1.0, v35
	v_rcp_f32_e32 v34, v34
	v_rcp_f32_e32 v35, v35
	s_nop 0
	v_pk_mul_f32 v[30:31], v[30:31], v[34:35]
	s_nop 0
	v_pk_mul_f32 v[26:27], v[26:27], v[30:31]
	s_nop 0
	v_cvt_pk_bf16_f32 v26, v26, v27
	v_mul_f32_e32 v27, 0xbfb8aa3b, v32
	v_exp_f32_e32 v27, v27
	s_nop 0
	v_add_f32_e32 v27, 1.0, v27
	v_rcp_f32_e32 v30, v27
	v_mul_f32_e32 v27, 0xbfb8aa3b, v33
	v_exp_f32_e32 v27, v27
	s_nop 0
	v_add_f32_e32 v27, 1.0, v27
	v_rcp_f32_e32 v31, v27
	s_nop 0
	v_pk_mul_f32 v[30:31], v[32:33], v[30:31]
	s_nop 0
	v_pk_mul_f32 v[28:29], v[28:29], v[30:31]
	s_nop 0
	v_cvt_pk_bf16_f32 v27, v28, v29
	v_mul_f32_e32 v28, 0xbfb8aa3b, v22
	v_mul_f32_e32 v29, 0xbfb8aa3b, v23
	v_exp_f32_e32 v28, v28
	v_exp_f32_e32 v29, v29
	v_add_f32_e32 v28, 1.0, v28
	v_add_f32_e32 v29, 1.0, v29
	v_rcp_f32_e32 v28, v28
	v_rcp_f32_e32 v29, v29
	s_nop 0
	v_pk_mul_f32 v[22:23], v[22:23], v[28:29]
	s_nop 0
	v_pk_mul_f32 v[18:19], v[18:19], v[22:23]
	s_nop 0
	v_cvt_pk_bf16_f32 v28, v18, v19
	v_mul_f32_e32 v18, 0xbfb8aa3b, v24
	v_mul_f32_e32 v19, 0xbfb8aa3b, v25
	v_exp_f32_e32 v18, v18
	v_exp_f32_e32 v19, v19
	v_add_f32_e32 v18, 1.0, v18
	v_add_f32_e32 v19, 1.0, v19
	v_rcp_f32_e32 v18, v18
	v_rcp_f32_e32 v19, v19
	s_nop 0
	v_pk_mul_f32 v[18:19], v[24:25], v[18:19]
	s_nop 0
	v_pk_mul_f32 v[18:19], v[20:21], v[18:19]
	s_nop 0
	v_cvt_pk_bf16_f32 v29, v18, v19
	v_add_co_u32_e32 v18, vcc, s14, v114
	s_nop 1
	v_addc_co_u32_e32 v19, vcc, 0, v115, vcc
	global_store_dwordx4 v[18:19], v[26:29], off
	v_mul_f32_e32 v18, 0xbfb8aa3b, v14
	v_mul_f32_e32 v19, 0xbfb8aa3b, v15
	v_exp_f32_e32 v18, v18
	v_exp_f32_e32 v19, v19
	v_add_f32_e32 v18, 1.0, v18
	v_add_f32_e32 v19, 1.0, v19
	v_rcp_f32_e32 v18, v18
	v_rcp_f32_e32 v19, v19
	s_nop 0
	v_pk_mul_f32 v[14:15], v[14:15], v[18:19]
	s_nop 0
	v_pk_mul_f32 v[10:11], v[10:11], v[14:15]
	s_nop 0
	v_cvt_pk_bf16_f32 v10, v10, v11
	v_mul_f32_e32 v11, 0xbfb8aa3b, v16
	v_exp_f32_e32 v11, v11
	s_nop 0
	v_add_f32_e32 v11, 1.0, v11
	v_rcp_f32_e32 v14, v11
	v_mul_f32_e32 v11, 0xbfb8aa3b, v17
	v_exp_f32_e32 v11, v11
	s_nop 0
	v_add_f32_e32 v11, 1.0, v11
	v_rcp_f32_e32 v15, v11
	s_nop 0
	v_pk_mul_f32 v[14:15], v[16:17], v[14:15]
	s_nop 0
	v_pk_mul_f32 v[12:13], v[12:13], v[14:15]
	s_nop 0
	v_cvt_pk_bf16_f32 v11, v12, v13
	v_mul_f32_e32 v12, 0xbfb8aa3b, v6
	v_mul_f32_e32 v13, 0xbfb8aa3b, v7
	v_exp_f32_e32 v12, v12
	v_exp_f32_e32 v13, v13
	v_add_f32_e32 v12, 1.0, v12
	v_add_f32_e32 v13, 1.0, v13
	v_rcp_f32_e32 v12, v12
	v_rcp_f32_e32 v13, v13
	s_nop 0
	v_pk_mul_f32 v[6:7], v[6:7], v[12:13]
	s_nop 0
	v_pk_mul_f32 v[2:3], v[2:3], v[6:7]
	s_nop 0
	v_cvt_pk_bf16_f32 v12, v2, v3
	v_mul_f32_e32 v2, 0xbfb8aa3b, v8
	v_mul_f32_e32 v3, 0xbfb8aa3b, v9
	v_exp_f32_e32 v2, v2
	v_exp_f32_e32 v3, v3
	v_add_f32_e32 v2, 1.0, v2
	v_add_f32_e32 v3, 1.0, v3
	v_rcp_f32_e32 v2, v2
	v_rcp_f32_e32 v3, v3
	s_nop 0
	v_pk_mul_f32 v[2:3], v[8:9], v[2:3]
	s_nop 0
	v_pk_mul_f32 v[2:3], v[4:5], v[2:3]
	s_nop 0
	v_cvt_pk_bf16_f32 v13, v2, v3
	v_add_co_u32_e32 v2, vcc, 0x16000, v114
	s_nop 1
	v_addc_co_u32_e32 v3, vcc, 0, v115, vcc
	global_store_dwordx4 v[2:3], v[10:13], off
	s_branch .LBB0_170
